# mlstm_seq: next-chunk loads use SGPR base + lane offset, one per MFMA gap instead of a burst after the barrier; stores likewise
# speedup vs baseline: 1.0143x; 1.0143x over previous
; #define LAS __attribute__((address_space(3)))
; #define MFMA32(a, b, c) __builtin_amdgcn_mfma_f32_32x32x16_bf16((a), (b), (c), 0, 0, 0)
; __device__ __forceinline__ void mlstm_seq(LAS unsigned char* lds, int tid_in, int b, int h, const bf16_t* z1, const bf16_t* z2a, const float* g_hnorm, bf16_t* yb, const unsigned char* ws) {
;     ...
;         f32x16 Z[2];
; #pragma unroll
;         for (int i = 0; i < 16; ++i) { Z[0][i] = 0.f; Z[1][i] = 0.f; }
; #pragma unroll
;         for (int dkb = 0; dkb < 4; ++dkb)
; #pragma unroll
;             for (int s2 = 0; s2 < 2; ++s2) {
;                 const bf16x8 ax = packacc8(X[dkb], 8 * s2);
; #pragma unroll
;                 for (int tb = 0; tb < 2; ++tb) {
;                     const LAS unsigned char* p = Qb + (32 * tb + r) * QS + (32 * dkb + 16 * s2 + 4 * hh) * 2;
;                     const u32x2 lo = *(const LAS u32x2*)p, hi = *(const LAS u32x2*)(p + 16);
;                     const u32x4 bq = {lo.x, lo.y, hi.x, hi.y};
;                     Z[tb] = MFMA32(ax, __builtin_bit_cast(bf16x8, bq), Z[tb]);
;                 }
;             }
;         { float f[16]; { float t8[8]; unpack8(*(const LAS u32x4*)(Qb + tq * QS + part * 32), t8);
; #pragma unroll
;               for (int e = 0; e < 8; ++e) f[e] = t8[e];
;               unpack8(*(const LAS u32x4*)(Qb + tq * QS + part * 32 + 16), t8);
; #pragma unroll
;               for (int e = 0; e < 8; ++e) f[8 + e] = t8[e]; }
;           float dq = 0.f;
; #pragma unroll
;           for (int j = 0; j < 4; ++j) { const f32x4 n4 = *(const LAS f32x4*)(NV + 16 * part + 4 * j); dq += (f[4 * j] * n4[0] + f[4 * j + 1] * n4[1]) + (f[4 * j + 2] * n4[2] + f[4 * j + 3] * n4[3]); }
;           dq += __shfl_xor(dq, 1); dq += __shfl_xor(dq, 2); dq += __shfl_xor(dq, 4);
;           if (part == 0) INV[tq] = 1.f / fmaxf(fabsf(dq + dq0), eq); }
.Lml_loop:
	v_add_u32_e32 v144, 0x2000, v208
	ds_read2_b64 v[146:149], v208 offset1:2
	ds_read2_b64 v[222:225], v144 offset0:64 offset1:66
	ds_read2_b64 v[230:233], v208 offset0:4 offset1:6
	ds_read2_b64 v[234:237], v144 offset0:68 offset1:70
	ds_read_b128 v[242:245], v209
	ds_read_b128 v[246:249], v209 offset:16
	ds_read_b128 v[238:241], v165
	v_cvt_pk_bf16_f32 v136, v2, v3
	v_cvt_pk_bf16_f32 v137, v4, v5
	v_cvt_pk_bf16_f32 v138, v6, v7
	v_cvt_pk_bf16_f32 v139, v8, v9
	s_nop 0
	s_waitcnt lgkmcnt(6)
	v_mfma_f32_32x32x16_bf16 v[82:97], v[136:139], v[146:149], 0
	ds_read2_b64 v[146:149], v208 offset0:8 offset1:10
	s_add_u32 s12, s66, 0x6068000
	s_addc_u32 s13, s67, 0
	global_load_dwordx4 v[98:101], v176, s[12:13] offset:2560
	v_cvt_pk_bf16_f32 v140, v10, v11
	v_cvt_pk_bf16_f32 v141, v12, v13
	v_cvt_pk_bf16_f32 v142, v14, v15
	v_cvt_pk_bf16_f32 v143, v16, v17
	s_waitcnt lgkmcnt(6)
	v_mfma_f32_32x32x16_bf16 v[66:81], v[136:139], v[222:225], 0
	ds_read2_b64 v[222:225], v144 offset0:72 offset1:74
	s_add_u32 s12, s66, 0x6069000
	s_addc_u32 s13, s67, 0
	global_load_dwordx4 v[102:105], v176, s[12:13] offset:512
	s_waitcnt lgkmcnt(2)
	v_lshlrev_b32_e32 v134, 16, v242
	v_and_b32_e32 v135, 0xffff0000, v242
	v_lshlrev_b32_e32 v226, 16, v243
	v_and_b32_e32 v227, 0xffff0000, v243
	v_mul_f32_e32 v135, v239, v135
	v_mul_f32_e32 v227, v241, v227
	v_fmac_f32_e32 v135, v238, v134
	v_fmac_f32_e32 v227, v240, v226
	ds_read_b128 v[238:241], v165 offset:16
	v_add_f32_e32 v135, v135, v227
	v_add_f32_e32 v229, 0, v135
	v_mfma_f32_32x32x16_bf16 v[82:97], v[140:143], v[230:233], v[82:97]
	ds_read2_b64 v[230:233], v208 offset0:12 offset1:14
	s_add_u32 s12, s66, s8
	s_addc_u32 s13, s67, s9
	global_load_dword v215, v1, s[12:13]
	v_cvt_pk_bf16_f32 v136, v18, v19
	v_cvt_pk_bf16_f32 v137, v20, v21
	v_cvt_pk_bf16_f32 v138, v22, v23
	v_cvt_pk_bf16_f32 v139, v24, v25
	v_mfma_f32_32x32x16_bf16 v[66:81], v[140:143], v[234:237], v[66:81]
	ds_read2_b64 v[234:237], v144 offset0:76 offset1:78
	s_add_u32 s12, s66, 0x609c000
	s_addc_u32 s13, s67, 0
	global_load_dwordx4 v[106:109], v176, s[12:13] offset:2560
	s_waitcnt lgkmcnt(4)
	v_mfma_f32_32x32x16_bf16 v[82:97], v[136:139], v[146:149], v[82:97]
	ds_read2_b64 v[146:149], v208 offset0:16 offset1:18
	s_add_u32 s12, s66, 0x609d000
	s_addc_u32 s13, s67, 0
	global_load_dwordx4 v[110:113], v176, s[12:13] offset:512
	v_cvt_pk_bf16_f32 v140, v26, v27
	v_cvt_pk_bf16_f32 v141, v28, v29
	v_cvt_pk_bf16_f32 v142, v30, v31
	v_cvt_pk_bf16_f32 v143, v32, v33
	s_waitcnt lgkmcnt(4)
	v_mfma_f32_32x32x16_bf16 v[66:81], v[136:139], v[222:225], v[66:81]
	ds_read2_b64 v[222:225], v144 offset0:80 offset1:82
	s_add_u32 s12, s66, 0x10880000
	s_addc_u32 s13, s67, 0
	global_load_dwordx4 v[114:117], v172, s[12:13]
	s_waitcnt lgkmcnt(4)
	v_lshlrev_b32_e32 v134, 16, v244
	v_and_b32_e32 v135, 0xffff0000, v244
	v_lshlrev_b32_e32 v226, 16, v245
	v_and_b32_e32 v227, 0xffff0000, v245
	v_mul_f32_e32 v135, v239, v135
	v_mul_f32_e32 v227, v241, v227
	v_fmac_f32_e32 v135, v238, v134
	v_fmac_f32_e32 v227, v240, v226
	ds_read_b128 v[238:241], v165 offset:32
	v_add_f32_e32 v135, v135, v227
	v_add_f32_e32 v229, v229, v135
	s_waitcnt lgkmcnt(4)
	v_mfma_f32_32x32x16_bf16 v[82:97], v[140:143], v[230:233], v[82:97]
	ds_read2_b64 v[230:233], v208 offset0:20 offset1:22
	s_add_u32 s12, s66, 0x108a0000
	s_addc_u32 s13, s67, 0
	global_load_dwordx4 v[118:121], v172, s[12:13]
	v_cvt_pk_bf16_f32 v136, v34, v35
	v_cvt_pk_bf16_f32 v137, v36, v37
	v_cvt_pk_bf16_f32 v138, v38, v39
	v_cvt_pk_bf16_f32 v139, v40, v41
	s_waitcnt lgkmcnt(4)
	v_mfma_f32_32x32x16_bf16 v[66:81], v[140:143], v[234:237], v[66:81]
	ds_read2_b64 v[234:237], v144 offset0:84 offset1:86
	s_add_u32 s12, s66, 0x108c0000
	s_addc_u32 s13, s67, 0
	global_load_dwordx4 v[122:125], v172, s[12:13]
	s_waitcnt lgkmcnt(4)
	v_mfma_f32_32x32x16_bf16 v[82:97], v[136:139], v[146:149], v[82:97]
	ds_read2_b64 v[146:149], v208 offset0:24 offset1:26
	s_add_u32 s12, s66, 0x108e0000
	s_addc_u32 s13, s67, 0
	global_load_dwordx4 v[126:129], v172, s[12:13]
	v_cvt_pk_bf16_f32 v140, v42, v43
	v_cvt_pk_bf16_f32 v141, v44, v45
	v_cvt_pk_bf16_f32 v142, v46, v47
	v_cvt_pk_bf16_f32 v143, v48, v49
	s_waitcnt lgkmcnt(4)
	v_mfma_f32_32x32x16_bf16 v[66:81], v[136:139], v[222:225], v[66:81]
	ds_read2_b64 v[222:225], v144 offset0:88 offset1:90
	global_load_dwordx4 v[130:133], v162, s[66:67]
	s_waitcnt lgkmcnt(4)
	v_lshlrev_b32_e32 v134, 16, v246
	v_and_b32_e32 v135, 0xffff0000, v246
	v_lshlrev_b32_e32 v226, 16, v247
	v_and_b32_e32 v227, 0xffff0000, v247
	v_mul_f32_e32 v135, v239, v135
	v_mul_f32_e32 v227, v241, v227
	v_fmac_f32_e32 v135, v238, v134
	v_fmac_f32_e32 v227, v240, v226
	ds_read_b128 v[238:241], v165 offset:48
	v_add_f32_e32 v135, v135, v227
	v_add_f32_e32 v229, v229, v135
	s_waitcnt lgkmcnt(4)
	v_mfma_f32_32x32x16_bf16 v[82:97], v[140:143], v[230:233], v[82:97]
	ds_read2_b64 v[230:233], v208 offset0:28 offset1:30
	s_add_u32 s12, s66, 0x10881000
	s_addc_u32 s13, s67, 0
	global_load_dwordx4 v[182:185], v150, s[12:13]
	v_cvt_pk_bf16_f32 v136, v50, v51
	v_cvt_pk_bf16_f32 v137, v52, v53
	v_cvt_pk_bf16_f32 v138, v54, v55
	v_cvt_pk_bf16_f32 v139, v56, v57
	s_waitcnt lgkmcnt(4)
	v_mfma_f32_32x32x16_bf16 v[66:81], v[140:143], v[234:237], v[66:81]
	ds_read2_b64 v[234:237], v144 offset0:92 offset1:94
	s_add_u32 s12, s66, 0x108a1000
	s_addc_u32 s13, s67, 0
	global_load_dwordx4 v[186:189], v150, s[12:13]
	s_waitcnt lgkmcnt(4)
	v_mfma_f32_32x32x16_bf16 v[82:97], v[136:139], v[146:149], v[82:97]
	s_add_u32 s12, s66, 0x108c1000
	s_addc_u32 s13, s67, 0
	global_load_dwordx4 v[190:193], v150, s[12:13]
	v_cvt_pk_bf16_f32 v140, v58, v59
	v_cvt_pk_bf16_f32 v141, v60, v61
	v_cvt_pk_bf16_f32 v142, v62, v63
	v_cvt_pk_bf16_f32 v143, v64, v65
	s_waitcnt lgkmcnt(3)
; #define LAS __attribute__((address_space(3)))
; #define MFMA32(a, b, c) __builtin_amdgcn_mfma_f32_32x32x16_bf16((a), (b), (c), 0, 0, 0)
; __device__ __forceinline__ s16x4 trread(const LAS unsigned char* p) { return __builtin_bit_cast(s16x4, __builtin_amdgcn_ds_read_tr16_b64_v4i16((LAS v4i16_t*)p)); }
; __device__ __forceinline__ bf16x8 cat44(s16x4 lo, s16x4 hi) { return (bf16x8){lo[0], lo[1], lo[2], lo[3], hi[0], hi[1], hi[2], hi[3]}; }
; __device__ __forceinline__ void mlstm_seq(LAS unsigned char* lds, int tid_in, int b, int h, const bf16_t* z1, const bf16_t* z2a, const float* g_hnorm, bf16_t* yb, const unsigned char* ws) {
;     ...
;                     const u32x2 lo = *(const LAS u32x2*)p, hi = *(const LAS u32x2*)(p + 16);
;                     const u32x4 bq = {lo.x, lo.y, hi.x, hi.y};
;                     Z[tb] = MFMA32(ax, __builtin_bit_cast(bf16x8, bq), Z[tb]);
;                 }
;             }
;         { float f[16]; { float t8[8]; unpack8(*(const LAS u32x4*)(Qb + tq * QS + part * 32), t8);
; #pragma unroll
;               for (int e = 0; e < 8; ++e) f[e] = t8[e];
;               unpack8(*(const LAS u32x4*)(Qb + tq * QS + part * 32 + 16), t8);
; #pragma unroll
;               for (int e = 0; e < 8; ++e) f[8 + e] = t8[e]; }
;           float dq = 0.f;
; #pragma unroll
;           for (int j = 0; j < 4; ++j) { const f32x4 n4 = *(const LAS f32x4*)(NV + 16 * part + 4 * j); dq += (f[4 * j] * n4[0] + f[4 * j + 1] * n4[1]) + (f[4 * j + 2] * n4[2] + f[4 * j + 3] * n4[3]); }
;           dq += __shfl_xor(dq, 1); dq += __shfl_xor(dq, 2); dq += __shfl_xor(dq, 4);
;           if (part == 0) INV[tq] = 1.f / fmaxf(fabsf(dq + dq0), eq); }
;         bf16x8 vf[4];
; #pragma unroll
;         for (int ks = 0; ks < 4; ++ks) {
;             const LAS unsigned char* p = Vb + (16 * ks + 8 * hh + q4) * VS + (32 * wid + 16 * (g4 & 1) + 4 * p4) * 2;
;             vf[ks] = cat44(trread(p), trread(p + 4 * VS));
	v_mfma_f32_32x32x16_bf16 v[66:81], v[136:139], v[222:225], v[66:81]
	s_add_u32 s12, s66, 0x108e1000
	s_addc_u32 s13, s67, 0
	global_load_dwordx4 v[194:197], v150, s[12:13]
	s_waitcnt lgkmcnt(2)
	v_lshlrev_b32_e32 v134, 16, v248
	v_and_b32_e32 v135, 0xffff0000, v248
	v_lshlrev_b32_e32 v226, 16, v249
	v_and_b32_e32 v227, 0xffff0000, v249
	v_mul_f32_e32 v135, v239, v135
	v_mul_f32_e32 v227, v241, v227
	v_fmac_f32_e32 v135, v238, v134
	v_fmac_f32_e32 v227, v240, v226
	v_add_f32_e32 v135, v135, v227
	v_add_f32_e32 v229, v229, v135
	s_waitcnt lgkmcnt(1)
	v_mfma_f32_32x32x16_bf16 v[82:97], v[140:143], v[230:233], v[82:97]
	s_add_u32 s12, s66, 0x1dc80000
	s_addc_u32 s13, s67, 0
	global_load_dword v217, v170, s[12:13] offset:2048
	s_waitcnt lgkmcnt(0)
	v_mfma_f32_32x32x16_bf16 v[66:81], v[140:143], v[234:237], v[66:81]
	s_add_u32 s12, s66, 0x1de80000
	s_addc_u32 s13, s67, 0
	global_load_dword v218, v170, s[12:13] offset:2048
	v_add_f32_dpp v229, v229, v229 quad_perm:[1,0,3,2] row_mask:0xf bank_mask:0xf
	ds_read_b64_tr_b16 v[146:147], v210 offset:37888
	ds_read_b64_tr_b16 v[148:149], v210 offset:40192
	ds_read_b128 v[222:225], v212
	v_add_f32_dpp v229, v229, v229 quad_perm:[2,3,0,1] row_mask:0xf bank_mask:0xf
	ds_read_b64_tr_b16 v[140:141], v210 offset:47104
	ds_read_b64_tr_b16 v[142:143], v210 offset:49408
	ds_read_b128 v[230:233], v212 offset:32
	ds_read_b64_tr_b16 v[136:137], v210 offset:56320
	ds_read_b64_tr_b16 v[138:139], v210 offset:58624
	ds_read_b128 v[234:237], v212 offset:64
	ds_read_b64_tr_b16 v[242:243], v211 offset:56320
	ds_read_b64_tr_b16 v[244:245], v211 offset:58624
	ds_read_b128 v[238:241], v212 offset:96
	ds_read_b128 v[246:249], v212 offset:4608
	v_add_f32_dpp v229, v229, v229 row_half_mirror row_mask:0xf bank_mask:0xf
	s_and_saveexec_b64 s[12:13], s[42:43]
	s_cbranch_execz .Lml_dskip
	v_add_f32_e32 v135, v251, v229
	v_max_f32_e32 v134, v250, v250
	v_max_f32_e64 v134, |v135|, v134
	v_div_scale_f32 v135, s[16:17], v134, v134, 1.0
	v_rcp_f32_e32 v226, v135
	s_nop 0
	v_fma_f32 v227, -v135, v226, 1.0
	v_fmac_f32_e32 v226, v227, v226
	v_div_scale_f32 v227, vcc, 1.0, v134, 1.0
	v_mul_f32_e32 v145, v227, v226
	v_fma_f32 v229, -v135, v145, v227
	v_fmac_f32_e32 v145, v229, v226
	v_fma_f32 v135, -v135, v145, v227
	v_div_fmas_f32 v135, v135, v226, v145
	v_div_fixup_f32 v134, v135, v134, 1.0
	ds_write_b32 v198, v134
; #define LAS __attribute__((address_space(3)))
; #define MFMA32(a, b, c) __builtin_amdgcn_mfma_f32_32x32x16_bf16((a), (b), (c), 0, 0, 0)
; __device__ __forceinline__ s16x4 trread(const LAS unsigned char* p) { return __builtin_bit_cast(s16x4, __builtin_amdgcn_ds_read_tr16_b64_v4i16((LAS v4i16_t*)p)); }
; __device__ __forceinline__ bf16x8 cat44(s16x4 lo, s16x4 hi) { return (bf16x8){lo[0], lo[1], lo[2], lo[3], hi[0], hi[1], hi[2], hi[3]}; }
; __device__ __forceinline__ void mlstm_seq(LAS unsigned char* lds, int tid_in, int b, int h, const bf16_t* z1, const bf16_t* z2a, const float* g_hnorm, bf16_t* yb, const unsigned char* ws) {
;     ...
; #pragma unroll
;         for (int tb = 0; tb < 2; ++tb)
; #pragma unroll
;             for (int ks = 0; ks < 4; ++ks) {
;                 const bf16x8 bs = *(const LAS bf16x8*)(SCb + (32 * tb + r) * SS + (16 * ks + 8 * hh) * 2);
;                 Z[tb] = MFMA32(vf[ks], bs, Z[tb]);
;             }
;         { float p0 = 0.f, p1 = 0.f;
; #pragma unroll
;           for (int i = 0; i < 16; ++i) { p0 += Z[0][i] * Z[0][i]; p1 += Z[1][i] * Z[1][i]; }
;           p0 += __shfl_xor(p0, 32); p1 += __shfl_xor(p1, 32);
;           if (hh == 0) { PR[r * 8 + wid] = p0; PR[(32 + r) * 8 + wid] = p1; } }
; #pragma unroll
;         for (int dkb = 0; dkb < 4; ++dkb) {
; #pragma unroll
;             for (int i = 0; i < 16; ++i) X[dkb][i] *= decay;
; #pragma unroll
;             for (int ks = 0; ks < 4; ++ks) {
;                 const LAS unsigned char* p = KUb + (16 * ks + 8 * hh + q4) * US + (32 * dkb + 16 * (g4 & 1) + 4 * p4) * 2;
;                 X[dkb] = MFMA32(cat44(trread(p), trread(p + 4 * US)), vf[ks], X[dkb]);
;             }
;         }
.Lml_dskip:
	s_or_b64 exec, exec, s[12:13]
	v_xor_b32_e32 v144, 32, v220
	v_lshlrev_b32_e32 v144, 2, v144
	s_nop 1
	s_waitcnt lgkmcnt(10)
	v_mfma_f32_32x32x16_bf16 v[82:97], v[146:149], v[222:225], v[82:97]
	ds_read_b128 v[222:225], v212 offset:4640
	global_load_dword v219, v160, s[66:67]
	s_waitcnt lgkmcnt(8)
	v_mfma_f32_32x32x16_bf16 v[82:97], v[140:143], v[230:233], v[82:97]
	ds_read_b128 v[230:233], v212 offset:4672
	s_waitcnt lgkmcnt(6)
	v_mfma_f32_32x32x16_bf16 v[82:97], v[136:139], v[234:237], v[82:97]
	ds_read_b128 v[234:237], v212 offset:4704
	s_waitcnt lgkmcnt(4)
	v_mfma_f32_32x32x16_bf16 v[82:97], v[242:245], v[238:241], v[82:97]
	ds_read_b64_tr_b16 v[238:239], v213 offset:17408
	ds_read_b64_tr_b16 v[240:241], v213 offset:18688
	s_waitcnt lgkmcnt(5)
	v_mfma_f32_32x32x16_bf16 v[66:81], v[146:149], v[246:249], v[66:81]
	ds_read_b64_tr_b16 v[246:247], v213 offset:22528
	ds_read_b64_tr_b16 v[248:249], v213 offset:23808
	v_pk_mul_f32 v[2:3], v[2:3], v[164:165] op_sel_hi:[1,0]
	v_pk_mul_f32 v[4:5], v[4:5], v[164:165] op_sel_hi:[1,0]
	v_pk_mul_f32 v[6:7], v[6:7], v[164:165] op_sel_hi:[1,0]
	v_pk_mul_f32 v[8:9], v[8:9], v[164:165] op_sel_hi:[1,0]
	s_waitcnt lgkmcnt(6)
	v_mfma_f32_32x32x16_bf16 v[66:81], v[140:143], v[222:225], v[66:81]
	ds_read_b64_tr_b16 v[222:223], v213 offset:27648
	ds_read_b64_tr_b16 v[224:225], v213 offset:28928
	v_pk_mul_f32 v[10:11], v[10:11], v[164:165] op_sel_hi:[1,0]
	v_pk_mul_f32 v[12:13], v[12:13], v[164:165] op_sel_hi:[1,0]
	v_pk_mul_f32 v[14:15], v[14:15], v[164:165] op_sel_hi:[1,0]
	v_pk_mul_f32 v[16:17], v[16:17], v[164:165] op_sel_hi:[1,0]
	s_waitcnt lgkmcnt(7)
	v_mfma_f32_32x32x16_bf16 v[66:81], v[136:139], v[230:233], v[66:81]
	ds_read_b64_tr_b16 v[230:231], v213 offset:32768
	ds_read_b64_tr_b16 v[232:233], v213 offset:34048
	s_waitcnt lgkmcnt(8)
	v_mfma_f32_32x32x16_bf16 v[66:81], v[242:245], v[234:237], v[66:81]
	ds_read_b64_tr_b16 v[234:235], v213 offset:17472
	ds_read_b64_tr_b16 v[236:237], v213 offset:18752
	s_waitcnt lgkmcnt(8)
	v_mfma_f32_32x32x16_bf16 v[2:17], v[238:241], v[146:149], v[2:17]
	ds_read_b64_tr_b16 v[238:239], v213 offset:22592
	ds_read_b64_tr_b16 v[240:241], v213 offset:23872
	v_mul_f32_e32 v134, v82, v82
	v_fmac_f32_e32 v134, v83, v83
	v_fmac_f32_e32 v134, v84, v84
	v_fmac_f32_e32 v134, v85, v85
	v_fmac_f32_e32 v134, v86, v86
	v_fmac_f32_e32 v134, v87, v87
	v_pk_mul_f32 v[18:19], v[18:19], v[164:165] op_sel_hi:[1,0]
	v_pk_mul_f32 v[20:21], v[20:21], v[164:165] op_sel_hi:[1,0]
	s_waitcnt lgkmcnt(8)
	v_mfma_f32_32x32x16_bf16 v[2:17], v[246:249], v[140:143], v[2:17]
	ds_read_b64_tr_b16 v[246:247], v213 offset:27712
	ds_read_b64_tr_b16 v[248:249], v213 offset:28992
	v_fmac_f32_e32 v134, v88, v88
	v_fmac_f32_e32 v134, v89, v89
	v_fmac_f32_e32 v134, v90, v90
	v_fmac_f32_e32 v134, v91, v91
	v_fmac_f32_e32 v134, v92, v92
	v_fmac_f32_e32 v134, v93, v93
	v_pk_mul_f32 v[22:23], v[22:23], v[164:165] op_sel_hi:[1,0]
	v_pk_mul_f32 v[24:25], v[24:25], v[164:165] op_sel_hi:[1,0]
	v_pk_mul_f32 v[26:27], v[26:27], v[164:165] op_sel_hi:[1,0]
	s_waitcnt lgkmcnt(8)
	v_mfma_f32_32x32x16_bf16 v[2:17], v[222:225], v[136:139], v[2:17]
	ds_read_b64_tr_b16 v[222:223], v213 offset:32832
	ds_read_b64_tr_b16 v[224:225], v213 offset:34112
	v_fmac_f32_e32 v134, v94, v94
	v_fmac_f32_e32 v134, v95, v95
	v_fmac_f32_e32 v134, v96, v96
	v_fmac_f32_e32 v134, v97, v97
	v_pk_mul_f32 v[28:29], v[28:29], v[164:165] op_sel_hi:[1,0]
	v_pk_mul_f32 v[30:31], v[30:31], v[164:165] op_sel_hi:[1,0]
	v_pk_mul_f32 v[32:33], v[32:33], v[164:165] op_sel_hi:[1,0]
	s_waitcnt lgkmcnt(8)
	v_mfma_f32_32x32x16_bf16 v[2:17], v[230:233], v[242:245], v[2:17]
	ds_read_b64_tr_b16 v[230:231], v213 offset:17536
	ds_read_b64_tr_b16 v[232:233], v213 offset:18816
	v_mul_f32_e32 v135, v66, v66
	v_fmac_f32_e32 v135, v67, v67
	v_fmac_f32_e32 v135, v68, v68
	v_fmac_f32_e32 v135, v69, v69
	v_fmac_f32_e32 v135, v70, v70
	v_fmac_f32_e32 v135, v71, v71
	s_waitcnt lgkmcnt(8)
	v_mfma_f32_32x32x16_bf16 v[18:33], v[234:237], v[146:149], v[18:33]
	ds_read_b64_tr_b16 v[234:235], v213 offset:22656
	ds_read_b64_tr_b16 v[236:237], v213 offset:23936
	v_fmac_f32_e32 v135, v72, v72
	v_fmac_f32_e32 v135, v73, v73
	v_fmac_f32_e32 v135, v74, v74
	v_fmac_f32_e32 v135, v75, v75
	v_fmac_f32_e32 v135, v76, v76
	v_pk_mul_f32 v[34:35], v[34:35], v[164:165] op_sel_hi:[1,0]
	v_pk_mul_f32 v[36:37], v[36:37], v[164:165] op_sel_hi:[1,0]
	s_waitcnt lgkmcnt(8)
	v_mfma_f32_32x32x16_bf16 v[18:33], v[238:241], v[140:143], v[18:33]
	ds_read_b64_tr_b16 v[238:239], v213 offset:27776
	ds_read_b64_tr_b16 v[240:241], v213 offset:29056
	v_fmac_f32_e32 v135, v77, v77
	v_fmac_f32_e32 v135, v78, v78
	v_fmac_f32_e32 v135, v79, v79
	v_fmac_f32_e32 v135, v80, v80
	v_fmac_f32_e32 v135, v81, v81
	v_pk_mul_f32 v[38:39], v[38:39], v[164:165] op_sel_hi:[1,0]
	v_pk_mul_f32 v[40:41], v[40:41], v[164:165] op_sel_hi:[1,0]
	v_pk_mul_f32 v[42:43], v[42:43], v[164:165] op_sel_hi:[1,0]
	s_waitcnt lgkmcnt(8)
	v_mfma_f32_32x32x16_bf16 v[18:33], v[246:249], v[136:139], v[18:33]
	ds_read_b64_tr_b16 v[246:247], v213 offset:32896
	ds_read_b64_tr_b16 v[248:249], v213 offset:34176
	ds_bpermute_b32 v226, v144, v134
	ds_bpermute_b32 v227, v144, v135
	v_pk_mul_f32 v[44:45], v[44:45], v[164:165] op_sel_hi:[1,0]
	v_pk_mul_f32 v[46:47], v[46:47], v[164:165] op_sel_hi:[1,0]
	v_pk_mul_f32 v[48:49], v[48:49], v[164:165] op_sel_hi:[1,0]
	s_waitcnt lgkmcnt(10)
	v_mfma_f32_32x32x16_bf16 v[18:33], v[222:225], v[242:245], v[18:33]
	ds_read_b64_tr_b16 v[222:223], v213 offset:17600
	ds_read_b64_tr_b16 v[224:225], v213 offset:18880
	v_pk_mul_f32 v[50:51], v[50:51], v[164:165] op_sel_hi:[1,0]
	v_pk_mul_f32 v[52:53], v[52:53], v[164:165] op_sel_hi:[1,0]
	v_pk_mul_f32 v[54:55], v[54:55], v[164:165] op_sel_hi:[1,0]
	s_waitcnt lgkmcnt(10)
	v_mfma_f32_32x32x16_bf16 v[34:49], v[230:233], v[146:149], v[34:49]
	ds_read_b64_tr_b16 v[230:231], v213 offset:22720
	ds_read_b64_tr_b16 v[232:233], v213 offset:24000
	v_pk_mul_f32 v[56:57], v[56:57], v[164:165] op_sel_hi:[1,0]
	v_pk_mul_f32 v[58:59], v[58:59], v[164:165] op_sel_hi:[1,0]
	v_pk_mul_f32 v[60:61], v[60:61], v[164:165] op_sel_hi:[1,0]
	s_waitcnt lgkmcnt(10)
	v_mfma_f32_32x32x16_bf16 v[34:49], v[234:237], v[140:143], v[34:49]
	ds_read_b64_tr_b16 v[234:235], v213 offset:27840
	ds_read_b64_tr_b16 v[236:237], v213 offset:29120
	v_pk_mul_f32 v[62:63], v[62:63], v[164:165] op_sel_hi:[1,0]
	v_pk_mul_f32 v[64:65], v[64:65], v[164:165] op_sel_hi:[1,0]
	s_waitcnt lgkmcnt(10)
	v_mfma_f32_32x32x16_bf16 v[34:49], v[238:241], v[136:139], v[34:49]
	ds_read_b64_tr_b16 v[238:239], v213 offset:32960
	ds_read_b64_tr_b16 v[240:241], v213 offset:34240
	s_waitcnt lgkmcnt(8)
	s_and_saveexec_b64 s[12:13], s[44:45]
	s_cbranch_execz .Lml_prskip
	v_add_f32_e32 v135, v135, v227
	v_add_f32_e32 v134, v134, v226
	ds_write2st64_b32 v200, v134, v135 offset1:4

; #define LAS __attribute__((address_space(3)))
; __device__ __forceinline__ float bflo(unsigned w) { return __uint_as_float(w << 16); }
; __device__ __forceinline__ float bfhi(unsigned w) { return __uint_as_float(w & 0xffff0000u); }
; __device__ __forceinline__ unsigned pk2(float lo, float hi) { return pg8::cvt_pk_bf16(lo, hi); }
; #define LDS_WAIT() asm volatile("s_waitcnt lgkmcnt(0)" ::: "memory")
; __device__ __forceinline__ void mlstm_seq(LAS unsigned char* lds, int tid_in, int b, int h, const bf16_t* z1, const bf16_t* z2a, const float* g_hnorm, bf16_t* yb, const unsigned char* ws) {
;     ...
;         const float decay = pdec;
; #pragma unroll
;         for (int i = 0; i < 2; ++i) { *(LAS u32x4*)(Qb + (srow + 32 * i) * QS + sc16 * 16) = pq[i]; *(LAS u32x4*)(KUb + (srow + 32 * i) * US + sc16 * 16) = pk[i]; }
; #pragma unroll
;         for (int i = 0; i < 4; ++i) *(LAS u32x4*)(Vb + (vrow + 16 * i) * VS + vc * 16) = pv[i];
;         *(LAS u32x4*)(SCb + (tid >> 3) * SS + (tid & 7) * 16) = psc;
;     ...
;         LDS_WAIT(); __builtin_amdgcn_s_barrier(); asm volatile("" ::: "memory");
;         if (tid < 128) NV[tid] = decay * NV[tid] + dn;
; #pragma unroll
;         for (int tb = 0; tb < 2; ++tb) {
;             const int t = 32 * tb + r;
;             const float inv = INV[t];
;             const f32x4 pa = *(const LAS f32x4*)(PR + t * 8), pb = *(const LAS f32x4*)(PR + t * 8 + 4);
;             const float rn = inv * rsqrtf(inv * inv * ((pa[0] + pa[1]) + (pa[2] + pa[3]) + (pb[0] + pb[1]) + (pb[2] + pb[3])) * (1.f / 256.f) + EPSN);
; #pragma unroll
;             for (int g = 0; g < 4; ++g) {
;                 const int dv = 32 * wid + 8 * g + 4 * hh;
;                 u32x2 w; w.x = pk2(Z[tb][4 * g] * rn * bflo(zo[tb][g].x), Z[tb][4 * g + 1] * rn * bfhi(zo[tb][g].x));
;                 w.y = pk2(Z[tb][4 * g + 2] * rn * bflo(zo[tb][g].y), Z[tb][4 * g + 3] * rn * bfhi(zo[tb][g].y));
;                 *(u32x2*)(yb + (tok0 + t) * Z2_LD + h * 256 + dv) = w;
;             }
;         }
.Lml_nvskip:
	s_or_b64 exec, exec, s[12:13]
	s_add_u32 s8, s8, 4
	s_addc_u32 s9, s9, 0
	s_mov_b64 s[16:17], 0x800
	s_waitcnt lgkmcnt(0)
	s_cmp_eq_u32 s14, 1
	s_cbranch_scc1 .Lml_nostage
	s_waitcnt vmcnt(7)
	ds_write_b128 v0, v[98:101]
	ds_write_b128 v206, v[102:105] offset:17408
	ds_write_b128 v0, v[106:109] offset:8704
	ds_write_b128 v206, v[110:113] offset:27648
	ds_write_b128 v202, v[114:117] offset:37888
	ds_write_b128 v202, v[118:121] offset:47104
	ds_write_b128 v202, v[122:125] offset:56320
	ds_write_b128 v203, v[126:129] offset:27648
	ds_write_b128 v207, v[130:133]
.Lml_nostage:
	v_mul_f32_e32 v140, v226, v226
	v_add_f32_e32 v141, v223, v222
	v_add_f32_e32 v142, v224, v225
	v_add_f32_e32 v143, v232, v233
	v_add_f32_e32 v146, v230, v231
	v_add_f32_e32 v141, v141, v142
	v_add_f32_e32 v141, v141, v146
	v_add_f32_e32 v141, v143, v141
	v_mul_f32_e32 v141, v140, v141
	v_fmamk_f32 v141, v141, 0x3b800000, v221
	v_mul_f32_e32 v142, 0x4b800000, v141
	v_cmp_gt_f32_e32 vcc, s77, v141
	s_nop 1
	v_cndmask_b32_e32 v141, v141, v142, vcc
	v_rsq_f32_e32 v141, v141
	s_nop 0
	v_mul_f32_e32 v142, 0x45800000, v141
	v_cndmask_b32_e32 v141, v141, v142, vcc
	v_mul_f32_e32 v145, v226, v141
	v_mul_f32_e32 v82, v82, v145
	v_lshlrev_b32_e32 v140, 16, v180
	v_mul_f32_e32 v83, v83, v145
	v_and_b32_e32 v141, 0xffff0000, v180
	v_mul_f32_e32 v82, v82, v140
	v_mul_f32_e32 v83, v83, v141
	v_mul_f32_e32 v84, v84, v145
	v_lshlrev_b32_e32 v142, 16, v181
	v_mul_f32_e32 v85, v85, v145
	v_and_b32_e32 v143, 0xffff0000, v181
	v_mul_f32_e32 v84, v84, v142
	v_mul_f32_e32 v85, v85, v143
	v_mul_f32_e32 v86, v86, v145
	v_lshlrev_b32_e32 v140, 16, v178
	v_mul_f32_e32 v87, v87, v145
	v_and_b32_e32 v141, 0xffff0000, v178
	v_mul_f32_e32 v86, v86, v140
	v_mul_f32_e32 v87, v87, v141
	v_mul_f32_e32 v88, v88, v145
	v_lshlrev_b32_e32 v142, 16, v179
	v_mul_f32_e32 v89, v89, v145
	v_and_b32_e32 v143, 0xffff0000, v179
	v_mul_f32_e32 v88, v88, v142
	v_mul_f32_e32 v89, v89, v143
	v_cvt_pk_bf16_f32 v82, v82, v83
	v_cvt_pk_bf16_f32 v83, v84, v85
	v_cvt_pk_bf16_f32 v84, v86, v87
	v_cvt_pk_bf16_f32 v85, v88, v89
	s_nop 1
	v_permlane32_swap_b32_e32 v82, v84
	v_permlane32_swap_b32_e32 v83, v85
	v_mul_f32_e32 v90, v90, v145
	v_lshlrev_b32_e32 v140, 16, v174
	v_mul_f32_e32 v91, v91, v145
	v_and_b32_e32 v141, 0xffff0000, v174
	v_mul_f32_e32 v90, v90, v140
	v_mul_f32_e32 v91, v91, v141
	v_mul_f32_e32 v92, v92, v145
	v_lshlrev_b32_e32 v142, 16, v175
	v_mul_f32_e32 v93, v93, v145
	v_and_b32_e32 v143, 0xffff0000, v175
	v_mul_f32_e32 v92, v92, v142
	v_mul_f32_e32 v93, v93, v143
	v_mul_f32_e32 v94, v94, v145
	v_lshlrev_b32_e32 v140, 16, v166
	v_mul_f32_e32 v95, v95, v145
	v_and_b32_e32 v141, 0xffff0000, v166
	v_mul_f32_e32 v94, v94, v140
	v_mul_f32_e32 v95, v95, v141
	v_mul_f32_e32 v96, v96, v145
	v_lshlrev_b32_e32 v142, 16, v167
	v_mul_f32_e32 v97, v97, v145
	v_and_b32_e32 v143, 0xffff0000, v167
	v_mul_f32_e32 v96, v96, v142
	v_mul_f32_e32 v97, v97, v143
	v_cvt_pk_bf16_f32 v90, v90, v91
	v_cvt_pk_bf16_f32 v91, v92, v93
	v_cvt_pk_bf16_f32 v92, v94, v95
	v_cvt_pk_bf16_f32 v93, v96, v97
	s_nop 1
	v_permlane32_swap_b32_e32 v90, v92
	v_permlane32_swap_b32_e32 v91, v93
	s_nop 0
	v_permlane16_swap_b32_e32 v82, v90
	v_permlane16_swap_b32_e32 v83, v91
	v_permlane16_swap_b32_e32 v84, v92
	v_permlane16_swap_b32_e32 v85, v93
	s_add_u32 s12, s66, 0x10800000
	s_addc_u32 s13, s67, 0
	global_store_dwordx4 v168, v[82:85], s[12:13]
	s_add_u32 s12, s66, 0x10820000
	s_addc_u32 s13, s67, 0
	global_store_dwordx4 v168, v[90:93], s[12:13]
	v_mul_f32_e32 v140, v227, v227
	v_add_f32_e32 v141, v235, v234
	v_add_f32_e32 v142, v236, v237
	v_add_f32_e32 v143, v248, v249
	v_add_f32_e32 v146, v246, v247
	v_add_f32_e32 v141, v141, v142
	v_add_f32_e32 v141, v141, v146
	v_add_f32_e32 v141, v143, v141
	v_mul_f32_e32 v141, v140, v141
	v_fmamk_f32 v141, v141, 0x3b800000, v221
	v_mul_f32_e32 v142, 0x4b800000, v141
	v_cmp_gt_f32_e32 vcc, s77, v141
	s_nop 1
	v_cndmask_b32_e32 v141, v141, v142, vcc
	v_rsq_f32_e32 v141, v141
	s_nop 0
	v_mul_f32_e32 v142, 0x45800000, v141
	v_cndmask_b32_e32 v141, v141, v142, vcc
	v_mul_f32_e32 v145, v227, v141
	v_mul_f32_e32 v66, v66, v145
	v_lshlrev_b32_e32 v140, 16, v158
	v_mul_f32_e32 v67, v67, v145
	v_and_b32_e32 v141, 0xffff0000, v158
	v_mul_f32_e32 v66, v66, v140
	v_mul_f32_e32 v67, v67, v141
	v_mul_f32_e32 v68, v68, v145
	v_lshlrev_b32_e32 v142, 16, v159
	v_mul_f32_e32 v69, v69, v145
	v_and_b32_e32 v143, 0xffff0000, v159
	v_mul_f32_e32 v68, v68, v142
	v_mul_f32_e32 v69, v69, v143
	v_mul_f32_e32 v70, v70, v145
	v_lshlrev_b32_e32 v140, 16, v156
	v_mul_f32_e32 v71, v71, v145
	v_and_b32_e32 v141, 0xffff0000, v156
	v_mul_f32_e32 v70, v70, v140
	v_mul_f32_e32 v71, v71, v141
	v_mul_f32_e32 v72, v72, v145
	v_lshlrev_b32_e32 v142, 16, v157
	v_mul_f32_e32 v73, v73, v145
	v_and_b32_e32 v143, 0xffff0000, v157
	v_mul_f32_e32 v72, v72, v142
	v_mul_f32_e32 v73, v73, v143
	v_cvt_pk_bf16_f32 v66, v66, v67
	v_cvt_pk_bf16_f32 v67, v68, v69
	v_cvt_pk_bf16_f32 v68, v70, v71
	v_cvt_pk_bf16_f32 v69, v72, v73
	s_nop 1
	v_permlane32_swap_b32_e32 v66, v68
	v_permlane32_swap_b32_e32 v67, v69
	v_mul_f32_e32 v74, v74, v145
	v_lshlrev_b32_e32 v140, 16, v154
	v_mul_f32_e32 v75, v75, v145
	v_and_b32_e32 v141, 0xffff0000, v154
	v_mul_f32_e32 v74, v74, v140
	v_mul_f32_e32 v75, v75, v141
	v_mul_f32_e32 v76, v76, v145
	v_lshlrev_b32_e32 v142, 16, v155
	v_mul_f32_e32 v77, v77, v145
	v_and_b32_e32 v143, 0xffff0000, v155
	v_mul_f32_e32 v76, v76, v142
	v_mul_f32_e32 v77, v77, v143
	v_mul_f32_e32 v78, v78, v145
	v_lshlrev_b32_e32 v140, 16, v152
	v_mul_f32_e32 v79, v79, v145
	v_and_b32_e32 v141, 0xffff0000, v152
	v_mul_f32_e32 v78, v78, v140
	v_mul_f32_e32 v79, v79, v141
	v_mul_f32_e32 v80, v80, v145
	v_lshlrev_b32_e32 v142, 16, v153
	v_mul_f32_e32 v81, v81, v145
	v_and_b32_e32 v143, 0xffff0000, v153
	v_mul_f32_e32 v80, v80, v142
	v_mul_f32_e32 v81, v81, v143
	v_cvt_pk_bf16_f32 v74, v74, v75
	v_cvt_pk_bf16_f32 v75, v76, v77
	v_cvt_pk_bf16_f32 v76, v78, v79
	v_cvt_pk_bf16_f32 v77, v80, v81
	s_nop 1
	v_permlane32_swap_b32_e32 v74, v76
	v_permlane32_swap_b32_e32 v75, v77
	s_nop 0
	v_permlane16_swap_b32_e32 v66, v74
	v_permlane16_swap_b32_e32 v67, v75
	v_permlane16_swap_b32_e32 v68, v76
	v_permlane16_swap_b32_e32 v69, v77
	s_add_u32 s12, s66, 0x10840000
	s_addc_u32 s13, s67, 0
	global_store_dwordx4 v168, v[66:69], s[12:13]
	s_add_u32 s12, s66, 0x10860000
	s_addc_u32 s13, s67, 0
	global_store_dwordx4 v168, v[74:77], s[12:13]
	s_mov_b64 s[12:13], 0x80000
	v_lshl_add_u64 v[160:161], v[160:161], 0, s[92:93]
	v_lshl_add_u64 v[162:163], v[162:163], 0, s[94:95]
	v_lshl_add_u64 v[150:151], v[150:151], 0, s[12:13]
	v_lshl_add_u64 v[172:173], v[172:173], 0, s[12:13]
	v_lshl_add_u64 v[168:169], v[168:169], 0, s[12:13]
	s_mov_b64 s[12:13], 0x68000
	v_lshl_add_u64 v[170:171], v[170:171], 0, s[16:17]
	v_lshl_add_u64 v[176:177], v[176:177], 0, s[12:13]
	s_add_i32 s14, s14, -1
	s_waitcnt vmcnt(4)
; __device__ __forceinline__ void mlstm_seq(LAS unsigned char* lds, int tid_in, int b, int h, const bf16_t* z1, const bf16_t* z2a, const float* g_hnorm, bf16_t* yb, const unsigned char* ws) {
;     ...
;         u32x2 zo[2][4];
; #pragma unroll
;         for (int tb = 0; tb < 2; ++tb)
; #pragma unroll
;             for (int g = 0; g < 4; ++g) zo[tb][g] = pzo[tb][g];
;         const float wi0 = pwi0, wi1 = pwi1, wq = pwq, eq = peq, dq0 = pdq, dn = pdn;
	v_permlane16_swap_b32_e32 v182, v186
	v_permlane16_swap_b32_e32 v183, v187
	v_permlane16_swap_b32_e32 v184, v188
	v_permlane16_swap_b32_e32 v185, v189
	v_permlane16_swap_b32_e32 v190, v194
	v_permlane16_swap_b32_e32 v191, v195
	v_permlane16_swap_b32_e32 v192, v196
	v_permlane16_swap_b32_e32 v193, v197
	v_permlane32_swap_b32_e32 v182, v184
	v_permlane32_swap_b32_e32 v183, v185
	v_permlane32_swap_b32_e32 v186, v188
	v_permlane32_swap_b32_e32 v187, v189
	v_permlane32_swap_b32_e32 v190, v192
	v_permlane32_swap_b32_e32 v191, v193
	v_permlane32_swap_b32_e32 v194, v196
	v_permlane32_swap_b32_e32 v195, v197
	v_mov_b64_e32 v[180:181], v[182:183]
	v_mov_b64_e32 v[178:179], v[184:185]
	v_mov_b64_e32 v[174:175], v[186:187]
	v_mov_b64_e32 v[166:167], v[188:189]
	v_mov_b64_e32 v[158:159], v[190:191]
	v_mov_b64_e32 v[156:157], v[192:193]
	v_mov_b64_e32 v[154:155], v[194:195]
	v_mov_b64_e32 v[152:153], v[196:197]
	v_mov_b32_e32 v250, v217
	v_mov_b32_e32 v251, v218
	v_mov_b32_e32 v216, v219
	v_mov_b32_e32 v164, v215
	s_cmp_eq_u32 s14, 0
	s_cbranch_scc1 .LBB0_93
	s_waitcnt lgkmcnt(0)
	s_barrier
	s_branch .Lml_loop
	s_nop 0
	s_nop 0
	s_nop 0
	s_nop 0
	s_nop 0
	s_nop 0
	s_nop 0
	s_nop 0
	s_nop 0
	s_nop 0
	s_nop 0
	s_nop 0
	s_nop 0
	s_nop 0
	s_nop 0
	s_nop 0
	s_nop 0
	s_nop 0
	s_nop 0
	s_nop 0
	s_nop 0
	s_nop 0
	s_nop 0
	s_nop 0
